# LRU item step-3 scan and carry fix-up: per-token LDS reads hoisted ahead of the dependent chain (same arithmetic order)
# speedup vs baseline: 1.0448x; 1.0030x over previous
; #define MFMA32(a, b, c) __builtin_amdgcn_mfma_f32_32x32x16_bf16((a), (b), (c), 0, 0, 0)
; DI int crow(int e, int h) { return (e & 3) + 8 * (e >> 2) + 4 * h; }
; DI void lru_item(const Params& P, const WsPtrs& W, int layer, int item, unsigned char* smem) {
;     ...
;       __syncthreads();
;       {
;         f32x16 ra, rx;
; #pragma unroll
;         for (int e = 0; e < 16; ++e) { ra[e] = 0.f; rx[e] = 0.f; }
; #pragma unroll
;         for (int ks = 0; ks < 4; ++ks) {
;           bf16x8 xa = *(const bf16x8*)(XCb + (32 * tm + r) * 72 + 16 * ks + 8 * h);
;           bf16x8 wa = *(const bf16x8*)(WaT + (32 * tn + r) * 72 + 16 * ks + 8 * h);
;           bf16x8 wx = *(const bf16x8*)(WxT + (32 * tn + r) * 72 + 16 * ks + 8 * h);
;           ra = MFMA32(xa, wa, ra);
;           rx = MFMA32(xa, wx, rx);
;         }
; #pragma unroll
;         for (int e = 0; e < 16; ++e) {
;           int tk = 32 * tm + crow(e, h);
;           float rg = __builtin_amdgcn_rcpf(1.f + __builtin_amdgcn_exp2f(-LOG2E * (ra[e] + ba)));
;           float ig = __builtin_amdgcn_rcpf(1.f + __builtin_amdgcn_exp2f(-LOG2E * (rx[e] + bx)));
;           float a = __builtin_amdgcn_exp2f(-LOG2E * rg * sp);
;           float xcv = XU[tk * 68 + cl];
;           float u = __builtin_amdgcn_sqrtf(fmaxf(1.f - a * a, 0.f)) * ig * xcv;
;           AA[tk * 68 + cl] = a; XU[tk * 68 + cl] = u;
;         }
;       }
.LBB0_643:
	s_waitcnt lgkmcnt(0)
	s_barrier
	ds_read_b128 v[2:5], v127
	ds_read_b128 v[6:9], v128
	s_mov_b64 s[70:71], -1
	s_waitcnt lgkmcnt(0)
	v_mfma_f32_32x32x16_bf16 v[18:33], v[2:5], v[6:9], 0
	ds_read_b128 v[6:9], v129
	ds_read_b128 v[90:93], v127 offset:32
	ds_read_b128 v[94:97], v128 offset:32
	s_and_b64 vcc, exec, s[24:25]
	s_waitcnt lgkmcnt(2)
	v_mfma_f32_32x32x16_bf16 v[2:17], v[2:5], v[6:9], 0
	s_waitcnt lgkmcnt(0)
	v_mfma_f32_32x32x16_bf16 v[18:33], v[90:93], v[94:97], v[18:33]
	ds_read_b128 v[94:97], v129 offset:32
	s_waitcnt lgkmcnt(0)
	v_mfma_f32_32x32x16_bf16 v[2:17], v[90:93], v[94:97], v[2:17]
	ds_read_b128 v[90:93], v127 offset:64
	ds_read_b128 v[94:97], v128 offset:64
	s_waitcnt lgkmcnt(0)
	v_mfma_f32_32x32x16_bf16 v[18:33], v[90:93], v[94:97], v[18:33]
	ds_read_b128 v[94:97], v129 offset:64
	s_waitcnt lgkmcnt(0)
	v_mfma_f32_32x32x16_bf16 v[2:17], v[90:93], v[94:97], v[2:17]
	ds_read_b128 v[90:93], v127 offset:96
	ds_read_b128 v[94:97], v128 offset:96
	s_waitcnt lgkmcnt(0)
	v_mfma_f32_32x32x16_bf16 v[18:33], v[90:93], v[94:97], v[18:33]
	ds_read_b128 v[94:97], v129 offset:96
	s_waitcnt lgkmcnt(0)
	v_mfma_f32_32x32x16_bf16 v[2:17], v[90:93], v[94:97], v[2:17]
	s_nop 8
	v_add_f32_e32 v18, v196, v18
	v_mul_f32_e32 v18, 0xbfb8aa3b, v18
	v_exp_f32_e32 v18, v18
	v_add_u32_e32 v91, 0x4800, v166
	v_add_f32_e32 v20, v196, v20
	v_mul_f32_e32 v20, 0xbfb8aa3b, v20
	v_add_f32_e32 v18, 1.0, v18
	v_rcp_f32_e32 v18, v18
	v_add_f32_e32 v2, v197, v2
	v_mul_f32_e32 v2, 0xbfb8aa3b, v2
	v_add_f32_e32 v3, v197, v3
	v_mul_f32_e32 v18, 0xbfb8aa3b, v18
	v_mul_f32_e32 v18, v198, v18
	v_exp_f32_e32 v90, v18
	v_add_f32_e32 v18, v196, v19
	v_mul_f32_e32 v18, 0xbfb8aa3b, v18
	v_exp_f32_e32 v92, v18
	v_exp_f32_e32 v2, v2
	v_mul_f32_e32 v3, 0xbfb8aa3b, v3
	v_exp_f32_e32 v3, v3
	v_add_f32_e32 v92, 1.0, v92
	v_rcp_f32_e32 v92, v92
	v_fma_f32 v93, -v90, v90, 1.0
	v_add_f32_e32 v2, 1.0, v2
	v_max_f32_e32 v93, 0, v93
	v_mul_f32_e32 v92, 0xbfb8aa3b, v92
	v_mul_f32_e32 v92, v198, v92
	v_exp_f32_e32 v92, v92
	v_rcp_f32_e32 v2, v2
	ds_read2_b32 v[18:19], v91 offset1:68
	v_sqrt_f32_e32 v93, v93
	v_fma_f32 v94, -v92, v92, 1.0
	v_add_f32_e32 v3, 1.0, v3
	v_max_f32_e32 v94, 0, v94
	v_rcp_f32_e32 v3, v3
	v_sqrt_f32_e32 v94, v94
	v_exp_f32_e32 v20, v20
	v_add_f32_e32 v4, v197, v4
	v_mul_f32_e32 v2, v2, v93
	v_mul_f32_e32 v3, v3, v94
	s_waitcnt lgkmcnt(0)
	v_mul_f32_e32 v18, v18, v2
	v_mul_f32_e32 v2, 0xbfb8aa3b, v4
	v_mul_f32_e32 v19, v19, v3
	v_exp_f32_e32 v2, v2
	v_add_f32_e32 v3, 1.0, v20
	v_rcp_f32_e32 v3, v3
	v_add_f32_e32 v5, v197, v5
	v_add_f32_e32 v2, 1.0, v2
	v_rcp_f32_e32 v4, v2
	v_mul_f32_e32 v2, 0xbfb8aa3b, v3
	v_mul_f32_e32 v2, v198, v2
	v_exp_f32_e32 v20, v2
	v_add_f32_e32 v2, v196, v21
	v_mul_f32_e32 v2, 0xbfb8aa3b, v2
	v_exp_f32_e32 v21, v2
	v_mul_f32_e32 v5, 0xbfb8aa3b, v5
	v_exp_f32_e32 v5, v5
	v_add_u32_e32 v95, 0xd000, v166
	v_add_f32_e32 v21, 1.0, v21
	v_rcp_f32_e32 v21, v21
	ds_write2_b32 v95, v90, v92 offset1:68
	v_fma_f32 v90, -v20, v20, 1.0
	v_max_f32_e32 v90, 0, v90
	v_mul_f32_e32 v21, 0xbfb8aa3b, v21
	v_mul_f32_e32 v21, v198, v21
	v_exp_f32_e32 v21, v21
	ds_read2_b32 v[2:3], v91 offset0:136 offset1:204
	v_sqrt_f32_e32 v90, v90
	v_add_f32_e32 v5, 1.0, v5
	v_fma_f32 v92, -v21, v21, 1.0
	v_max_f32_e32 v92, 0, v92
	v_rcp_f32_e32 v5, v5
	v_sqrt_f32_e32 v92, v92
	v_mul_f32_e32 v4, v4, v90
	s_waitcnt lgkmcnt(0)
	v_mul_f32_e32 v4, v2, v4
	ds_write2_b32 v91, v18, v19 offset1:68
	v_mul_f32_e32 v2, v5, v92
	v_mul_f32_e32 v5, v3, v2
	v_add_f32_e32 v2, v196, v22
	v_mul_f32_e32 v2, 0xbfb8aa3b, v2
	v_exp_f32_e32 v2, v2
	ds_write2_b32 v95, v20, v21 offset0:136 offset1:204
	v_add_f32_e32 v3, v197, v6
	v_mul_f32_e32 v3, 0xbfb8aa3b, v3
	v_add_f32_e32 v2, 1.0, v2
	v_rcp_f32_e32 v2, v2
	v_add_f32_e32 v7, v197, v7
	v_exp_f32_e32 v3, v3
	v_mul_f32_e32 v7, 0xbfb8aa3b, v7
	v_mul_f32_e32 v2, 0xbfb8aa3b, v2
	v_mul_f32_e32 v2, v198, v2
	v_exp_f32_e32 v18, v2
	v_add_f32_e32 v2, v196, v23
	v_mul_f32_e32 v2, 0xbfb8aa3b, v2
	v_exp_f32_e32 v20, v2
	v_exp_f32_e32 v7, v7
	v_fma_f32 v21, -v18, v18, 1.0
	v_add_f32_e32 v3, 1.0, v3
	v_add_f32_e32 v20, 1.0, v20
	v_rcp_f32_e32 v20, v20
	v_add_u32_e32 v19, 0x5000, v166
	v_max_f32_e32 v21, 0, v21
	v_rcp_f32_e32 v6, v3
	v_mul_f32_e32 v20, 0xbfb8aa3b, v20
	v_mul_f32_e32 v20, v198, v20
	v_exp_f32_e32 v20, v20
	ds_read2_b32 v[2:3], v19 offset0:32 offset1:100
	v_sqrt_f32_e32 v21, v21
	v_add_f32_e32 v7, 1.0, v7
	v_fma_f32 v22, -v20, v20, 1.0
	v_max_f32_e32 v22, 0, v22
	v_rcp_f32_e32 v7, v7
	v_sqrt_f32_e32 v22, v22
	ds_write2_b32 v91, v4, v5 offset0:136 offset1:204
	v_mul_f32_e32 v4, v6, v21
	s_waitcnt lgkmcnt(1)
	v_mul_f32_e32 v4, v4, v2
	v_mul_f32_e32 v2, v7, v22
	v_mul_f32_e32 v5, v2, v3
	v_add_f32_e32 v2, v196, v24
	v_mul_f32_e32 v2, 0xbfb8aa3b, v2
	v_exp_f32_e32 v2, v2
	v_add_f32_e32 v3, v197, v8
	v_add_u32_e32 v6, 0xd800, v166
	ds_write2_b32 v6, v18, v20 offset0:32 offset1:100
	v_add_f32_e32 v2, 1.0, v2
	v_rcp_f32_e32 v2, v2
	v_mul_f32_e32 v3, 0xbfb8aa3b, v3
	v_add_f32_e32 v9, v197, v9
	v_exp_f32_e32 v3, v3
	v_mul_f32_e32 v2, 0xbfb8aa3b, v2
	v_mul_f32_e32 v2, v198, v2
	v_exp_f32_e32 v8, v2
	v_add_f32_e32 v2, v196, v25
	v_mul_f32_e32 v2, 0xbfb8aa3b, v2
	v_exp_f32_e32 v18, v2
	v_mul_f32_e32 v9, 0xbfb8aa3b, v9
	v_exp_f32_e32 v9, v9
	v_fma_f32 v20, -v8, v8, 1.0
	v_add_f32_e32 v18, 1.0, v18
	v_rcp_f32_e32 v18, v18
	v_add_f32_e32 v3, 1.0, v3
	v_max_f32_e32 v20, 0, v20
	v_rcp_f32_e32 v7, v3
	v_mul_f32_e32 v18, 0xbfb8aa3b, v18
	v_mul_f32_e32 v18, v198, v18
	v_exp_f32_e32 v18, v18
	ds_read2_b32 v[2:3], v19 offset0:168 offset1:236
	v_sqrt_f32_e32 v20, v20
	v_add_f32_e32 v9, 1.0, v9
	v_fma_f32 v21, -v18, v18, 1.0
	v_max_f32_e32 v21, 0, v21
	v_rcp_f32_e32 v9, v9
	v_sqrt_f32_e32 v21, v21
	ds_write2_b32 v19, v4, v5 offset0:32 offset1:100
	v_mul_f32_e32 v4, v7, v20
	s_waitcnt lgkmcnt(1)
; DI int crow(int e, int h) { return (e & 3) + 8 * (e >> 2) + 4 * h; }
; DI void lru_item(const Params& P, const WsPtrs& W, int layer, int item, unsigned char* smem) {
;     ...
; #pragma unroll
;         for (int e = 0; e < 16; ++e) {
;           int tk = 32 * tm + crow(e, h);
;           float rg = __builtin_amdgcn_rcpf(1.f + __builtin_amdgcn_exp2f(-LOG2E * (ra[e] + ba)));
;           float ig = __builtin_amdgcn_rcpf(1.f + __builtin_amdgcn_exp2f(-LOG2E * (rx[e] + bx)));
;           float a = __builtin_amdgcn_exp2f(-LOG2E * rg * sp);
;           float xcv = XU[tk * 68 + cl];
;           float u = __builtin_amdgcn_sqrtf(fmaxf(1.f - a * a, 0.f)) * ig * xcv;
;           AA[tk * 68 + cl] = a; XU[tk * 68 + cl] = u;
;         }
;       }
;       __syncthreads();
	v_mul_f32_e32 v4, v4, v2
	v_mul_f32_e32 v2, v9, v21
	v_mul_f32_e32 v5, v2, v3
	v_add_f32_e32 v2, v196, v26
	v_mul_f32_e32 v2, 0xbfb8aa3b, v2
	v_exp_f32_e32 v2, v2
	v_add_f32_e32 v3, v197, v10
	v_mul_f32_e32 v3, 0xbfb8aa3b, v3
	v_add_f32_e32 v11, v197, v11
	v_add_f32_e32 v2, 1.0, v2
	v_rcp_f32_e32 v2, v2
	v_exp_f32_e32 v3, v3
	v_mul_f32_e32 v11, 0xbfb8aa3b, v11
	v_exp_f32_e32 v11, v11
	v_mul_f32_e32 v2, 0xbfb8aa3b, v2
	v_mul_f32_e32 v2, v198, v2
	v_exp_f32_e32 v7, v2
	v_add_f32_e32 v2, v196, v27
	v_mul_f32_e32 v2, 0xbfb8aa3b, v2
	v_exp_f32_e32 v9, v2
	v_fma_f32 v10, -v7, v7, 1.0
	ds_write2_b32 v6, v8, v18 offset0:168 offset1:236
	v_add_f32_e32 v3, 1.0, v3
	v_add_f32_e32 v9, 1.0, v9
	v_rcp_f32_e32 v9, v9
	v_add_u32_e32 v8, 0x5800, v166
	v_max_f32_e32 v10, 0, v10
	v_rcp_f32_e32 v6, v3
	v_mul_f32_e32 v9, 0xbfb8aa3b, v9
	v_mul_f32_e32 v9, v198, v9
	v_exp_f32_e32 v9, v9
	ds_read2_b32 v[2:3], v8 offset0:64 offset1:132
	v_sqrt_f32_e32 v10, v10
	v_add_f32_e32 v11, 1.0, v11
	v_fma_f32 v18, -v9, v9, 1.0
	v_max_f32_e32 v18, 0, v18
	v_rcp_f32_e32 v11, v11
	v_sqrt_f32_e32 v18, v18
	ds_write2_b32 v19, v4, v5 offset0:168 offset1:236
	v_mul_f32_e32 v4, v6, v10
	s_waitcnt lgkmcnt(1)
	v_mul_f32_e32 v4, v4, v2
	v_mul_f32_e32 v2, v11, v18
	v_mul_f32_e32 v5, v2, v3
	v_add_f32_e32 v3, v196, v28
	v_mul_f32_e32 v3, 0xbfb8aa3b, v3
	v_exp_f32_e32 v3, v3
	v_add_f32_e32 v6, v197, v12
	v_mul_f32_e32 v6, 0xbfb8aa3b, v6
	v_exp_f32_e32 v6, v6
	v_add_f32_e32 v3, 1.0, v3
	v_rcp_f32_e32 v3, v3
	v_add_u32_e32 v2, 0xe000, v166
	ds_write2_b32 v2, v7, v9 offset0:64 offset1:132
	v_add_f32_e32 v2, 1.0, v6
	v_rcp_f32_e32 v6, v2
	v_mul_f32_e32 v2, 0xbfb8aa3b, v3
	v_mul_f32_e32 v2, v198, v2
	v_exp_f32_e32 v7, v2
	v_add_f32_e32 v2, v196, v29
	v_mul_f32_e32 v2, 0xbfb8aa3b, v2
	v_exp_f32_e32 v10, v2
	v_add_f32_e32 v12, v197, v13
	v_mul_f32_e32 v12, 0xbfb8aa3b, v12
	v_exp_f32_e32 v12, v12
	v_add_f32_e32 v10, 1.0, v10
	v_rcp_f32_e32 v10, v10
	v_fma_f32 v11, -v7, v7, 1.0
	v_add_u32_e32 v9, 0x5a00, v166
	v_max_f32_e32 v11, 0, v11
	v_mul_f32_e32 v10, 0xbfb8aa3b, v10
	v_mul_f32_e32 v10, v198, v10
	v_exp_f32_e32 v10, v10
	ds_read2_b32 v[2:3], v9 offset0:72 offset1:140
	v_sqrt_f32_e32 v11, v11
	v_add_f32_e32 v12, 1.0, v12
	v_fma_f32 v13, -v10, v10, 1.0
	v_max_f32_e32 v13, 0, v13
	v_rcp_f32_e32 v12, v12
	v_sqrt_f32_e32 v13, v13
	ds_write2_b32 v8, v4, v5 offset0:64 offset1:132
	v_mul_f32_e32 v4, v6, v11
	s_waitcnt lgkmcnt(1)
	v_mul_f32_e32 v4, v4, v2
	v_mul_f32_e32 v2, v12, v13
	v_mul_f32_e32 v5, v2, v3
	v_add_f32_e32 v3, v196, v30
	v_mul_f32_e32 v3, 0xbfb8aa3b, v3
	v_exp_f32_e32 v3, v3
	v_add_f32_e32 v6, v197, v14
	v_mul_f32_e32 v6, 0xbfb8aa3b, v6
	v_exp_f32_e32 v6, v6
	v_add_f32_e32 v3, 1.0, v3
	v_rcp_f32_e32 v3, v3
	v_add_u32_e32 v2, 0xe200, v166
	ds_write2_b32 v2, v7, v10 offset0:72 offset1:140
	v_add_f32_e32 v2, 1.0, v6
	v_rcp_f32_e32 v6, v2
	v_mul_f32_e32 v2, 0xbfb8aa3b, v3
	v_mul_f32_e32 v2, v198, v2
	v_exp_f32_e32 v7, v2
	v_add_f32_e32 v2, v196, v31
	v_mul_f32_e32 v2, 0xbfb8aa3b, v2
	v_exp_f32_e32 v10, v2
	v_add_f32_e32 v12, v197, v15
	v_mul_f32_e32 v12, 0xbfb8aa3b, v12
	v_exp_f32_e32 v12, v12
	v_add_f32_e32 v10, 1.0, v10
	v_rcp_f32_e32 v10, v10
	v_fma_f32 v11, -v7, v7, 1.0
	v_add_u32_e32 v8, 0x6000, v166
	v_max_f32_e32 v11, 0, v11
	v_mul_f32_e32 v10, 0xbfb8aa3b, v10
	v_mul_f32_e32 v10, v198, v10
	v_exp_f32_e32 v10, v10
	ds_read2_b32 v[2:3], v8 offset0:96 offset1:164
	v_sqrt_f32_e32 v11, v11
	v_add_f32_e32 v12, 1.0, v12
	v_fma_f32 v13, -v10, v10, 1.0
	v_max_f32_e32 v13, 0, v13
	v_rcp_f32_e32 v12, v12
	v_sqrt_f32_e32 v13, v13
	ds_write2_b32 v9, v4, v5 offset0:72 offset1:140
	v_mul_f32_e32 v4, v6, v11
	s_waitcnt lgkmcnt(1)
	v_mul_f32_e32 v4, v4, v2
	v_mul_f32_e32 v2, v12, v13
	v_mul_f32_e32 v5, v2, v3
	v_add_f32_e32 v3, v196, v32
	v_mul_f32_e32 v3, 0xbfb8aa3b, v3
	v_exp_f32_e32 v3, v3
	v_add_f32_e32 v6, v197, v16
	v_mul_f32_e32 v6, 0xbfb8aa3b, v6
	v_exp_f32_e32 v6, v6
	v_add_f32_e32 v3, 1.0, v3
	v_rcp_f32_e32 v3, v3
	v_add_u32_e32 v2, 0xe800, v166
	ds_write2_b32 v2, v7, v10 offset0:96 offset1:164
	v_add_f32_e32 v2, 1.0, v6
	v_rcp_f32_e32 v6, v2
	v_mul_f32_e32 v2, 0xbfb8aa3b, v3
	v_mul_f32_e32 v2, v198, v2
	v_exp_f32_e32 v7, v2
	v_add_f32_e32 v2, v196, v33
	v_mul_f32_e32 v2, 0xbfb8aa3b, v2
	v_exp_f32_e32 v10, v2
	v_add_f32_e32 v12, v197, v17
	v_mul_f32_e32 v12, 0xbfb8aa3b, v12
	v_exp_f32_e32 v12, v12
	v_add_f32_e32 v10, 1.0, v10
	v_rcp_f32_e32 v10, v10
	v_fma_f32 v11, -v7, v7, 1.0
	v_add_u32_e32 v9, 0x6200, v166
	v_max_f32_e32 v11, 0, v11
	v_mul_f32_e32 v10, 0xbfb8aa3b, v10
	v_mul_f32_e32 v10, v198, v10
	v_exp_f32_e32 v10, v10
	ds_read2_b32 v[2:3], v9 offset0:104 offset1:172
	v_sqrt_f32_e32 v11, v11
	v_add_f32_e32 v12, 1.0, v12
	v_fma_f32 v13, -v10, v10, 1.0
	v_max_f32_e32 v13, 0, v13
	v_rcp_f32_e32 v12, v12
	v_sqrt_f32_e32 v13, v13
	ds_write2_b32 v8, v4, v5 offset0:96 offset1:164
	v_mul_f32_e32 v4, v6, v11
	s_waitcnt lgkmcnt(1)
	v_mul_f32_e32 v2, v4, v2
	v_mul_f32_e32 v4, v12, v13
	v_mul_f32_e32 v3, v4, v3
	v_add_u32_e32 v4, 0xea00, v166
	ds_write2_b32 v4, v7, v10 offset0:104 offset1:172
	ds_write2_b32 v9, v2, v3 offset0:104 offset1:172
	s_waitcnt lgkmcnt(0)
	s_barrier
; DI void lru_item(const Params& P, const WsPtrs& W, int layer, int item, unsigned char* smem) {
;     ...
;       {
;         float hc = 0.f, pc = 1.f;
; #pragma unroll
;         for (int i = 0; i < 16; ++i) {
;           const int io = 16 * w + i, tk = d ? 127 - io : io;
;           const float a = AA[tk * 68 + lane], u = XU[tk * 68 + lane];
;           hc = a * hc + u; pc = a * pc;
;           XU[tk * 68 + lane] = hc; AA[tk * 68 + lane] = pc;
;         }
;         SEG[w * 64 + lane] = hc; SEG[512 + w * 64 + lane] = pc;
;       }
;       __syncthreads();
;       {
;         float cin = carry, cmine = carry;
; #pragma unroll
;         for (int ww = 0; ww < 8; ++ww) {
;           if (ww == w) cmine = cin;
;           cin = SEG[512 + ww * 64 + lane] * cin + SEG[ww * 64 + lane];
;         }
;         carry = cin;
; #pragma unroll
;         for (int i = 0; i < 16; ++i) {
;           const int io = 16 * w + i, tk = d ? 127 - io : io;
;           XU[tk * 68 + lane] += AA[tk * 68 + lane] * cmine;
;         }
;       }
;       __syncthreads();
	ds_read2st64_b32 v[22:23], v199 offset0:72 offset1:208
	ds_read2st64_b32 v[24:25], v200 offset0:72 offset1:208
	ds_read2st64_b32 v[26:27], v201 offset0:72 offset1:208
	ds_read2st64_b32 v[28:29], v202 offset0:72 offset1:208
	ds_read2st64_b32 v[30:31], v203 offset0:72 offset1:208
	ds_read2st64_b32 v[32:33], v204 offset0:72 offset1:208
	ds_read2st64_b32 v[90:91], v205 offset0:72 offset1:208
	ds_read2st64_b32 v[92:93], v206 offset0:72 offset1:208
	ds_read2st64_b32 v[94:95], v207 offset0:72 offset1:208
	ds_read2st64_b32 v[96:97], v208 offset0:72 offset1:208
	ds_read2st64_b32 v[12:13], v209 offset0:72 offset1:208
	ds_read2st64_b32 v[14:15], v210 offset0:72 offset1:208
	ds_read2st64_b32 v[16:17], v211 offset0:72 offset1:208
	ds_read2st64_b32 v[8:9], v212 offset0:72 offset1:208
	ds_read2st64_b32 v[10:11], v213 offset0:72 offset1:208
	ds_read2st64_b32 v[18:19], v214 offset0:72 offset1:208
	v_or_b32_e32 v20, s20, v0
	v_or_b32_e32 v21, s21, v1
	v_lshl_add_u64 v[20:21], v[20:21], 0, v[104:105]
	s_waitcnt lgkmcnt(0)
	v_fma_f32 v22, 0, v23, v22
	ds_write_b32 v199, v22 offset:18432
	v_mul_f32_e32 v6, v23, v25
	v_fmac_f32_e32 v24, v22, v25
	ds_write2st64_b32 v200, v24, v6 offset0:72 offset1:208
	v_mul_f32_e32 v6, v6, v27
	v_fmac_f32_e32 v26, v24, v27
	ds_write2st64_b32 v201, v26, v6 offset0:72 offset1:208
	v_mul_f32_e32 v6, v6, v29
	v_fmac_f32_e32 v28, v26, v29
	ds_write2st64_b32 v202, v28, v6 offset0:72 offset1:208
	v_mul_f32_e32 v6, v6, v31
	v_fmac_f32_e32 v30, v28, v31
	ds_write2st64_b32 v203, v30, v6 offset0:72 offset1:208
	v_mul_f32_e32 v6, v6, v33
	v_fmac_f32_e32 v32, v30, v33
	ds_write2st64_b32 v204, v32, v6 offset0:72 offset1:208
	v_mul_f32_e32 v6, v6, v91
	v_fmac_f32_e32 v90, v32, v91
	ds_write2st64_b32 v205, v90, v6 offset0:72 offset1:208
	v_mul_f32_e32 v6, v6, v93
	v_fmac_f32_e32 v92, v90, v93
	ds_write2st64_b32 v206, v92, v6 offset0:72 offset1:208
	v_mul_f32_e32 v6, v6, v95
	v_fmac_f32_e32 v94, v92, v95
	ds_write2st64_b32 v207, v94, v6 offset0:72 offset1:208
	v_mul_f32_e32 v6, v6, v97
	v_fmac_f32_e32 v96, v94, v97
	ds_write2st64_b32 v208, v96, v6 offset0:72 offset1:208
	v_mul_f32_e32 v6, v6, v13
	v_fmac_f32_e32 v12, v96, v13
	ds_write2st64_b32 v209, v12, v6 offset0:72 offset1:208
	v_mul_f32_e32 v6, v6, v15
	v_fmac_f32_e32 v14, v12, v15
	ds_write2st64_b32 v210, v14, v6 offset0:72 offset1:208
	v_mul_f32_e32 v6, v6, v17
	v_fmac_f32_e32 v16, v14, v17
	ds_write2st64_b32 v211, v16, v6 offset0:72 offset1:208
	v_mul_f32_e32 v6, v6, v9
	v_fmac_f32_e32 v8, v16, v9
	ds_write2st64_b32 v212, v8, v6 offset0:72 offset1:208
	v_mul_f32_e32 v6, v6, v11
	v_fmac_f32_e32 v10, v8, v11
	ds_write2st64_b32 v213, v10, v6 offset0:72 offset1:208
	v_mul_f32_e32 v6, v6, v19
	v_fmac_f32_e32 v18, v10, v19
	ds_write2st64_b32 v214, v18, v6 offset0:72 offset1:208
	ds_write_b32 v131, v18
	ds_write_b32 v133, v6 offset:2048
	s_waitcnt lgkmcnt(0)
	s_barrier
	ds_read2st64_b32 v[22:23], v199 offset0:72 offset1:208
	ds_read2st64_b32 v[24:25], v200 offset0:72 offset1:208
	ds_read2st64_b32 v[26:27], v201 offset0:72 offset1:208
	ds_read2st64_b32 v[28:29], v202 offset0:72 offset1:208
	ds_read2st64_b32 v[30:31], v203 offset0:72 offset1:208
	ds_read2st64_b32 v[32:33], v204 offset0:72 offset1:208
	ds_read2st64_b32 v[90:91], v205 offset0:72 offset1:208
	ds_read2st64_b32 v[92:93], v206 offset0:72 offset1:208
	ds_read2st64_b32 v[94:95], v207 offset0:72 offset1:208
	ds_read2st64_b32 v[96:97], v208 offset0:72 offset1:208
	ds_read2st64_b32 v[12:13], v209 offset0:72 offset1:208
	ds_read2st64_b32 v[14:15], v210 offset0:72 offset1:208
	ds_read2st64_b32 v[16:17], v211 offset0:72 offset1:208
	ds_read2st64_b32 v[2:3], v132 offset0:8 offset1:9
	ds_read2st64_b32 v[4:5], v132 offset1:1
	ds_read2st64_b32 v[6:7], v132 offset0:2 offset1:3
	ds_read2st64_b32 v[8:9], v132 offset0:4 offset1:5
	s_waitcnt lgkmcnt(2)
	v_fma_f32 v2, v119, v2, v4
	v_cndmask_b32_e64 v4, v119, v2, s[6:7]
	v_fmac_f32_e32 v5, v2, v3
	ds_read2st64_b32 v[2:3], v132 offset0:10 offset1:11
	ds_read2st64_b32 v[10:11], v132 offset0:12 offset1:13
	ds_read2st64_b32 v[18:19], v132 offset0:14 offset1:15
	ds_read2st64_b32 v[118:119], v132 offset0:6 offset1:7
	v_cndmask_b32_e64 v4, v4, v5, s[8:9]
	s_waitcnt lgkmcnt(3)
	v_fma_f32 v2, v5, v2, v6
	v_cndmask_b32_e64 v4, v4, v2, s[10:11]
	v_fmac_f32_e32 v7, v2, v3
	v_cndmask_b32_e64 v2, v4, v7, s[12:13]
	s_waitcnt lgkmcnt(2)
	v_fma_f32 v4, v7, v10, v8
	v_cndmask_b32_e64 v5, v2, v4, s[14:15]
	v_fmac_f32_e32 v9, v4, v11
	v_cndmask_b32_e64 v4, v5, v9, s[16:17]
	s_waitcnt lgkmcnt(0)
	v_fma_f32 v18, v9, v18, v118
	v_cndmask_b32_e64 v4, v4, v18, s[18:19]
	ds_read2st64_b32 v[6:7], v212 offset0:72 offset1:208
	ds_read2st64_b32 v[8:9], v213 offset0:72 offset1:208
	ds_read2st64_b32 v[10:11], v214 offset0:72 offset1:208
	s_waitcnt lgkmcnt(3)
	v_fmac_f32_e32 v22, v4, v23
	ds_write_b32 v199, v22 offset:18432
	v_fmac_f32_e32 v24, v4, v25
	ds_write_b32 v200, v24 offset:18432
	v_fmac_f32_e32 v26, v4, v27
	ds_write_b32 v201, v26 offset:18432
	v_fmac_f32_e32 v28, v4, v29
	ds_write_b32 v202, v28 offset:18432
	v_fmac_f32_e32 v30, v4, v31
	ds_write_b32 v203, v30 offset:18432
	v_fmac_f32_e32 v32, v4, v33
	ds_write_b32 v204, v32 offset:18432
	v_fmac_f32_e32 v90, v4, v91
	ds_write_b32 v205, v90 offset:18432
	v_fmac_f32_e32 v92, v4, v93
	ds_write_b32 v206, v92 offset:18432
	v_fmac_f32_e32 v94, v4, v95
	ds_write_b32 v207, v94 offset:18432
	v_fmac_f32_e32 v96, v4, v97
	ds_write_b32 v208, v96 offset:18432
	v_fmac_f32_e32 v12, v4, v13
	ds_write_b32 v209, v12 offset:18432
	v_fmac_f32_e32 v14, v4, v15
	ds_write_b32 v210, v14 offset:18432
	v_fmac_f32_e32 v16, v4, v17
	ds_write_b32 v211, v16 offset:18432
	s_waitcnt lgkmcnt(13)
	v_fmac_f32_e32 v6, v4, v7
	ds_write_b32 v212, v6 offset:18432
	v_fmac_f32_e32 v8, v4, v9
	ds_write_b32 v213, v8 offset:18432
	v_fmac_f32_e32 v10, v4, v11
	ds_write_b32 v214, v10 offset:18432
	s_waitcnt lgkmcnt(0)
	s_barrier
; DI float bflo(u32 v) { return __uint_as_float(v << 16); }
; DI float bfhi(u32 v) { return __uint_as_float(v & 0xffff0000u); }
; DI float gelu_tanh(float x) { float z = 0.7978845608028654f * (x + 0.044715f * x * x * x); float t = 1.f - 2.f * __builtin_amdgcn_rcpf(__builtin_amdgcn_exp2f(2.f * LOG2E * z) + 1.f); return 0.5f * x * (1.f + t); }
; DI void lru_item(const Params& P, const WsPtrs& W, int layer, int item, unsigned char* smem) {
;     ...
;       {
;         const size_t trow = tokb + t0 + tt;
;         float hv[16];
; #pragma unroll
;         for (int q = 0; q < 4; ++q) { f32x4 v = *(const f32x4*)(XU + tt * 68 + cb16 + 4 * q); hv[4 * q] = v.x; hv[4 * q + 1] = v.y; hv[4 * q + 2] = v.z; hv[4 * q + 3] = v.w; }
;         float* hf = W.HF + trow * 1024 + c0 + cb16;
;         if (d == 0) {
; #pragma unroll
;           for (int q = 0; q < 4; ++q) *(f32x4*)(hf + 4 * q) = f32x4{hv[4 * q], hv[4 * q + 1], hv[4 * q + 2], hv[4 * q + 3]};
;         } else {
;           float gv[16] = {bflo(g0.x), bfhi(g0.x), bflo(g0.y), bfhi(g0.y), bflo(g0.z), bfhi(g0.z), bflo(g0.w), bfhi(g0.w),
;                           bflo(g1.x), bfhi(g1.x), bflo(g1.y), bfhi(g1.y), bflo(g1.z), bfhi(g1.z), bflo(g1.w), bfhi(g1.w)};
; #pragma unroll
;           for (int q = 0; q < 16; ++q) gv[q] = gelu_tanh(gv[q]);
; #pragma unroll
;           for (int q = 0; q < 4; ++q) {
;             f32x4 f = hfp[q];
;             hv[4 * q] = (hv[4 * q] + f.x) * gv[4 * q]; hv[4 * q + 1] = (hv[4 * q + 1] + f.y) * gv[4 * q + 1];
;             hv[4 * q + 2] = (hv[4 * q + 2] + f.z) * gv[4 * q + 2]; hv[4 * q + 3] = (hv[4 * q + 3] + f.w) * gv[4 * q + 3];
;           }
	ds_read_b128 v[2:5], v125 offset:18432
	ds_read_b128 v[6:9], v125 offset:18448
	ds_read_b128 v[10:13], v125 offset:18464
	ds_read_b128 v[14:17], v125 offset:18480
	s_cbranch_vccz .LBB0_645
	s_waitcnt vmcnt(4)
	v_lshlrev_b32_e32 v22, 16, v38
	v_mul_f32_e32 v0, 0x3d372713, v22
	v_mul_f32_e32 v0, v0, v22
	v_mov_b32_e32 v24, v22
	v_fmac_f32_e32 v24, v0, v24
	v_mul_f32_e32 v0, 0x3f4c422a, v24
	v_mul_f32_e32 v0, 0x4038aa3b, v0
	v_exp_f32_e32 v0, v0
	v_and_b32_e32 v23, 0xffff0000, v38
	v_mov_b32_e32 v25, v23
	s_waitcnt vmcnt(0) lgkmcnt(3)
	v_pk_add_f32 v[26:27], v[54:55], v[2:3]
	v_add_f32_e32 v0, 1.0, v0
	v_rcp_f32_e32 v24, v0
	v_mul_f32_e32 v0, 0x3d372713, v23
	v_mul_f32_e32 v0, v0, v23
	v_fmac_f32_e32 v25, v0, v25
	v_mul_f32_e32 v0, 0x3f4c422a, v25
	v_mul_f32_e32 v0, 0x4038aa3b, v0
	v_exp_f32_e32 v0, v0
	v_pk_mul_f32 v[22:23], v[22:23], 0.5 op_sel_hi:[1,0]
	s_waitcnt lgkmcnt(2)
	v_pk_add_f32 v[30:31], v[50:51], v[6:7]
	s_waitcnt lgkmcnt(1)
	v_pk_add_f32 v[90:91], v[46:47], v[10:11]
	v_add_f32_e32 v0, 1.0, v0
	v_rcp_f32_e32 v25, v0
	s_waitcnt lgkmcnt(0)
	v_pk_add_f32 v[94:95], v[42:43], v[14:15]
	s_mov_b64 s[70:71], 0
	v_pk_fma_f32 v[24:25], v[24:25], 2.0, 1.0 op_sel_hi:[1,0,0] neg_lo:[1,0,0] neg_hi:[1,0,0]
	s_nop 0
	v_pk_add_f32 v[24:25], v[24:25], 1.0 op_sel_hi:[1,0]
	s_nop 0
	v_pk_mul_f32 v[22:23], v[22:23], v[24:25]
	v_pk_add_f32 v[24:25], v[56:57], v[4:5]
	v_pk_mul_f32 v[22:23], v[22:23], v[26:27]
	v_lshlrev_b32_e32 v26, 16, v39
	v_mul_f32_e32 v0, 0x3d372713, v26
	v_mul_f32_e32 v0, v0, v26
	v_mov_b32_e32 v28, v26
	v_fmac_f32_e32 v28, v0, v28
	v_mul_f32_e32 v0, 0x3f4c422a, v28
	v_mul_f32_e32 v0, 0x4038aa3b, v0
	v_exp_f32_e32 v0, v0
	v_and_b32_e32 v27, 0xffff0000, v39
	v_mov_b32_e32 v29, v27
	v_cvt_pk_bf16_f32 v22, v22, v23
	v_add_f32_e32 v0, 1.0, v0
	v_rcp_f32_e32 v28, v0
	v_mul_f32_e32 v0, 0x3d372713, v27
	v_mul_f32_e32 v0, v0, v27
	v_fmac_f32_e32 v29, v0, v29
	v_mul_f32_e32 v0, 0x3f4c422a, v29
	v_mul_f32_e32 v0, 0x4038aa3b, v0
	v_exp_f32_e32 v0, v0
	v_pk_mul_f32 v[26:27], v[26:27], 0.5 op_sel_hi:[1,0]
	v_add_f32_e32 v0, 1.0, v0
	v_rcp_f32_e32 v29, v0
	s_nop 0
	v_pk_fma_f32 v[28:29], v[28:29], 2.0, 1.0 op_sel_hi:[1,0,0] neg_lo:[1,0,0] neg_hi:[1,0,0]
	s_nop 0
	v_pk_add_f32 v[28:29], v[28:29], 1.0 op_sel_hi:[1,0]
	s_nop 0
	v_pk_mul_f32 v[26:27], v[26:27], v[28:29]
	s_nop 0
	v_pk_mul_f32 v[24:25], v[26:27], v[24:25]
	v_lshlrev_b32_e32 v26, 16, v40
	v_mul_f32_e32 v0, 0x3d372713, v26
	v_mul_f32_e32 v0, v0, v26
	v_mov_b32_e32 v28, v26
	v_fmac_f32_e32 v28, v0, v28
	v_mul_f32_e32 v0, 0x3f4c422a, v28
	v_mul_f32_e32 v0, 0x4038aa3b, v0
	v_exp_f32_e32 v0, v0
	v_and_b32_e32 v27, 0xffff0000, v40
	v_mov_b32_e32 v29, v27
	v_cvt_pk_bf16_f32 v23, v24, v25
	v_add_f32_e32 v0, 1.0, v0
	v_rcp_f32_e32 v28, v0
	v_mul_f32_e32 v0, 0x3d372713, v27
	v_mul_f32_e32 v0, v0, v27
	v_fmac_f32_e32 v29, v0, v29
	v_mul_f32_e32 v0, 0x3f4c422a, v29
	v_mul_f32_e32 v0, 0x4038aa3b, v0
	v_exp_f32_e32 v0, v0
	v_pk_mul_f32 v[26:27], v[26:27], 0.5 op_sel_hi:[1,0]
	v_add_f32_e32 v0, 1.0, v0
	v_rcp_f32_e32 v29, v0
	s_nop 0
	v_pk_fma_f32 v[28:29], v[28:29], 2.0, 1.0 op_sel_hi:[1,0,0] neg_lo:[1,0,0] neg_hi:[1,0,0]
	s_nop 0
	v_pk_add_f32 v[28:29], v[28:29], 1.0 op_sel_hi:[1,0]
	s_nop 0
	v_pk_mul_f32 v[26:27], v[26:27], v[28:29]
	v_pk_add_f32 v[28:29], v[52:53], v[8:9]
	v_pk_mul_f32 v[26:27], v[26:27], v[30:31]
	v_lshlrev_b32_e32 v30, 16, v41
	v_mul_f32_e32 v0, 0x3d372713, v30
	v_mul_f32_e32 v0, v0, v30
	v_mov_b32_e32 v32, v30
	v_fmac_f32_e32 v32, v0, v32
	v_mul_f32_e32 v0, 0x3f4c422a, v32
	v_mul_f32_e32 v0, 0x4038aa3b, v0
	v_exp_f32_e32 v0, v0
	v_and_b32_e32 v31, 0xffff0000, v41
	v_mov_b32_e32 v33, v31
	v_cvt_pk_bf16_f32 v24, v26, v27
	v_add_f32_e32 v0, 1.0, v0
	v_rcp_f32_e32 v32, v0
	v_mul_f32_e32 v0, 0x3d372713, v31
	v_mul_f32_e32 v0, v0, v31
	v_fmac_f32_e32 v33, v0, v33
	v_mul_f32_e32 v0, 0x3f4c422a, v33
	v_mul_f32_e32 v0, 0x4038aa3b, v0
	v_exp_f32_e32 v0, v0
	v_pk_mul_f32 v[30:31], v[30:31], 0.5 op_sel_hi:[1,0]
	v_add_f32_e32 v0, 1.0, v0
	v_rcp_f32_e32 v33, v0
	s_nop 0
	v_pk_fma_f32 v[32:33], v[32:33], 2.0, 1.0 op_sel_hi:[1,0,0] neg_lo:[1,0,0] neg_hi:[1,0,0]
	s_nop 0
	v_pk_add_f32 v[32:33], v[32:33], 1.0 op_sel_hi:[1,0]
; DI u32 pack2(float a, float b) { f2_t v = {a, b}; bf2_t r = __builtin_convertvector(v, bf2_t); return __builtin_bit_cast(u32, r); }
; DI float bflo(u32 v) { return __uint_as_float(v << 16); }
; DI float bfhi(u32 v) { return __uint_as_float(v & 0xffff0000u); }
; DI float gelu_tanh(float x) { float z = 0.7978845608028654f * (x + 0.044715f * x * x * x); float t = 1.f - 2.f * __builtin_amdgcn_rcpf(__builtin_amdgcn_exp2f(2.f * LOG2E * z) + 1.f); return 0.5f * x * (1.f + t); }
; DI void lru_item(const Params& P, const WsPtrs& W, int layer, int item, unsigned char* smem) {
;     ...
;           float gv[16] = {bflo(g0.x), bfhi(g0.x), bflo(g0.y), bfhi(g0.y), bflo(g0.z), bfhi(g0.z), bflo(g0.w), bfhi(g0.w),
;                           bflo(g1.x), bfhi(g1.x), bflo(g1.y), bfhi(g1.y), bflo(g1.z), bfhi(g1.z), bflo(g1.w), bfhi(g1.w)};
; #pragma unroll
;           for (int q = 0; q < 16; ++q) gv[q] = gelu_tanh(gv[q]);
; #pragma unroll
;           for (int q = 0; q < 4; ++q) {
;             f32x4 f = hfp[q];
;             hv[4 * q] = (hv[4 * q] + f.x) * gv[4 * q]; hv[4 * q + 1] = (hv[4 * q + 1] + f.y) * gv[4 * q + 1];
;             hv[4 * q + 2] = (hv[4 * q + 2] + f.z) * gv[4 * q + 2]; hv[4 * q + 3] = (hv[4 * q + 3] + f.w) * gv[4 * q + 3];
;           }
;           u32x4 o0, o1;
;           o0.x = pack2(hv[0], hv[1]); o0.y = pack2(hv[2], hv[3]); o0.z = pack2(hv[4], hv[5]); o0.w = pack2(hv[6], hv[7]);
;           o1.x = pack2(hv[8], hv[9]); o1.y = pack2(hv[10], hv[11]); o1.z = pack2(hv[12], hv[13]); o1.w = pack2(hv[14], hv[15]);
;           u16* yo = W.YMIX + trow * 4096 + c0 + cb16;
;           *(u32x4*)yo = o0; *(u32x4*)(yo + 8) = o1;
	s_nop 0
	v_pk_mul_f32 v[30:31], v[30:31], v[32:33]
	s_nop 0
	v_pk_mul_f32 v[28:29], v[30:31], v[28:29]
	v_lshlrev_b32_e32 v30, 16, v34
	v_mul_f32_e32 v0, 0x3d372713, v30
	v_mul_f32_e32 v0, v0, v30
	v_mov_b32_e32 v32, v30
	v_fmac_f32_e32 v32, v0, v32
	v_mul_f32_e32 v0, 0x3f4c422a, v32
	v_mul_f32_e32 v0, 0x4038aa3b, v0
	v_exp_f32_e32 v0, v0
	v_and_b32_e32 v31, 0xffff0000, v34
	v_mov_b32_e32 v33, v31
	v_cvt_pk_bf16_f32 v25, v28, v29
	v_add_f32_e32 v0, 1.0, v0
	v_rcp_f32_e32 v32, v0
	v_mul_f32_e32 v0, 0x3d372713, v31
	v_mul_f32_e32 v0, v0, v31
	v_fmac_f32_e32 v33, v0, v33
	v_mul_f32_e32 v0, 0x3f4c422a, v33
	v_mul_f32_e32 v0, 0x4038aa3b, v0
	v_exp_f32_e32 v0, v0
	v_pk_mul_f32 v[30:31], v[30:31], 0.5 op_sel_hi:[1,0]
	v_add_f32_e32 v0, 1.0, v0
	v_rcp_f32_e32 v33, v0
	s_nop 0
	v_pk_fma_f32 v[32:33], v[32:33], 2.0, 1.0 op_sel_hi:[1,0,0] neg_lo:[1,0,0] neg_hi:[1,0,0]
	s_nop 0
	v_pk_add_f32 v[32:33], v[32:33], 1.0 op_sel_hi:[1,0]
	s_nop 0
	v_pk_mul_f32 v[30:31], v[30:31], v[32:33]
	v_pk_add_f32 v[32:33], v[48:49], v[12:13]
	v_pk_mul_f32 v[30:31], v[30:31], v[90:91]
	v_lshlrev_b32_e32 v90, 16, v35
	v_mul_f32_e32 v0, 0x3d372713, v90
	v_mul_f32_e32 v0, v0, v90
	v_mov_b32_e32 v92, v90
	v_fmac_f32_e32 v92, v0, v92
	v_mul_f32_e32 v0, 0x3f4c422a, v92
	v_mul_f32_e32 v0, 0x4038aa3b, v0
	v_exp_f32_e32 v0, v0
	v_and_b32_e32 v91, 0xffff0000, v35
	v_mov_b32_e32 v93, v91
	v_cvt_pk_bf16_f32 v26, v30, v31
	v_add_f32_e32 v0, 1.0, v0
	v_rcp_f32_e32 v92, v0
	v_mul_f32_e32 v0, 0x3d372713, v91
	v_mul_f32_e32 v0, v0, v91
	v_fmac_f32_e32 v93, v0, v93
	v_mul_f32_e32 v0, 0x3f4c422a, v93
	v_mul_f32_e32 v0, 0x4038aa3b, v0
	v_exp_f32_e32 v0, v0
	v_pk_mul_f32 v[90:91], v[90:91], 0.5 op_sel_hi:[1,0]
	v_lshlrev_b64 v[30:31], 13, v[20:21]
	v_lshl_add_u64 v[30:31], v[112:113], 0, v[30:31]
	v_add_f32_e32 v0, 1.0, v0
	v_rcp_f32_e32 v93, v0
	s_nop 0
	v_pk_fma_f32 v[92:93], v[92:93], 2.0, 1.0 op_sel_hi:[1,0,0] neg_lo:[1,0,0] neg_hi:[1,0,0]
	s_nop 0
	v_pk_add_f32 v[92:93], v[92:93], 1.0 op_sel_hi:[1,0]
	s_nop 0
	v_pk_mul_f32 v[90:91], v[90:91], v[92:93]
	s_nop 0
	v_pk_mul_f32 v[32:33], v[90:91], v[32:33]
	v_lshlrev_b32_e32 v90, 16, v36
	v_mul_f32_e32 v0, 0x3d372713, v90
	v_mul_f32_e32 v0, v0, v90
	v_mov_b32_e32 v92, v90
	v_fmac_f32_e32 v92, v0, v92
	v_mul_f32_e32 v0, 0x3f4c422a, v92
	v_mul_f32_e32 v0, 0x4038aa3b, v0
	v_exp_f32_e32 v0, v0
	v_and_b32_e32 v91, 0xffff0000, v36
	v_mov_b32_e32 v93, v91
	v_cvt_pk_bf16_f32 v27, v32, v33
	v_add_f32_e32 v0, 1.0, v0
	v_rcp_f32_e32 v92, v0
	v_mul_f32_e32 v0, 0x3d372713, v91
	v_mul_f32_e32 v0, v0, v91
	v_fmac_f32_e32 v93, v0, v93
	v_mul_f32_e32 v0, 0x3f4c422a, v93
	v_mul_f32_e32 v0, 0x4038aa3b, v0
	v_exp_f32_e32 v0, v0
	v_pk_mul_f32 v[90:91], v[90:91], 0.5 op_sel_hi:[1,0]
	v_add_f32_e32 v0, 1.0, v0
	v_rcp_f32_e32 v93, v0
	s_nop 0
	v_pk_fma_f32 v[92:93], v[92:93], 2.0, 1.0 op_sel_hi:[1,0,0] neg_lo:[1,0,0] neg_hi:[1,0,0]
	s_nop 0
	v_pk_add_f32 v[92:93], v[92:93], 1.0 op_sel_hi:[1,0]
	s_nop 0
	v_pk_mul_f32 v[90:91], v[90:91], v[92:93]
	v_pk_add_f32 v[92:93], v[44:45], v[16:17]
	v_pk_mul_f32 v[90:91], v[90:91], v[94:95]
	v_lshlrev_b32_e32 v94, 16, v37
	v_mul_f32_e32 v0, 0x3d372713, v94
	v_mul_f32_e32 v0, v0, v94
	v_mov_b32_e32 v96, v94
	v_fmac_f32_e32 v96, v0, v96
	v_mul_f32_e32 v0, 0x3f4c422a, v96
	v_mul_f32_e32 v0, 0x4038aa3b, v0
	v_exp_f32_e32 v0, v0
	v_and_b32_e32 v95, 0xffff0000, v37
	v_mov_b32_e32 v97, v95
	v_cvt_pk_bf16_f32 v28, v90, v91
	v_add_f32_e32 v0, 1.0, v0
	v_rcp_f32_e32 v96, v0
	v_mul_f32_e32 v0, 0x3d372713, v95
	v_mul_f32_e32 v0, v0, v95
	v_fmac_f32_e32 v97, v0, v97
	v_mul_f32_e32 v0, 0x3f4c422a, v97
	v_mul_f32_e32 v0, 0x4038aa3b, v0
	v_exp_f32_e32 v0, v0
	v_pk_mul_f32 v[94:95], v[94:95], 0.5 op_sel_hi:[1,0]
	v_add_f32_e32 v0, 1.0, v0
	v_rcp_f32_e32 v97, v0
	s_nop 0
	v_pk_fma_f32 v[96:97], v[96:97], 2.0, 1.0 op_sel_hi:[1,0,0] neg_lo:[1,0,0] neg_hi:[1,0,0]
	s_nop 0
	v_pk_add_f32 v[96:97], v[96:97], 1.0 op_sel_hi:[1,0]
	s_nop 0
	v_pk_mul_f32 v[94:95], v[94:95], v[96:97]
	s_nop 0
	v_pk_mul_f32 v[92:93], v[94:95], v[92:93]
	s_nop 0
	v_cvt_pk_bf16_f32 v29, v92, v93
	global_store_dwordx4 v[30:31], v[22:25], off
	global_store_dwordx4 v[30:31], v[26:29], off offset:16
